# same combination with the pre-scan code (P0..P4) moved 24 bytes to the placement phase that read fastest in the sweep
# baseline (speedup 1.0000x reference)
_Z10fwd_kernel4Args:
	s_nop 0
	s_nop 0
	s_nop 0
	s_nop 0
	s_nop 0
	s_nop 0
	s_load_dwordx2 s[28:29], s[0:1], 0x100
	v_readfirstlane_b32 s3, v0
	v_cmp_gt_u32_e32 vcc, 4, v0
	s_nop 0
	v_writelane_b32 v255, s3, 0
	s_and_saveexec_b64 s[4:5], vcc
	v_lshl_add_u32 v1, v0, 2, 0
	v_add_u32_e32 v1, 0x23040, v1
	v_mov_b32_e32 v2, 0
	ds_write_b32 v1, v2
	s_or_b64 exec, exec, s[4:5]
	s_load_dword s3, s[0:1], 0x108
	s_waitcnt lgkmcnt(0)
	s_barrier
	s_add_u32 s96, s28, 0xfdf0000
	s_getreg_b32 s4, hwreg(HW_REG_XCC_ID, 0, 4)
	s_addc_u32 s97, s29, 0
	s_and_b32 s95, s4, 15
	v_cmp_eq_u32_e64 s[6:7], 0, v0
	s_mov_b64 s[4:5], exec
	s_nop 0
	v_writelane_b32 v255, s6, 1
	s_nop 1
	v_writelane_b32 v255, s7, 2
	s_and_b64 s[6:7], s[4:5], s[6:7]
	s_mov_b64 exec, s[6:7]
	s_cbranch_execz .LBB0_5
	s_mov_b64 s[6:7], exec
	v_mbcnt_lo_u32_b32 v1, s6, 0
	v_mbcnt_hi_u32_b32 v1, s7, v1
	v_cmp_eq_u32_e32 vcc, 0, v1
	s_and_b64 s[8:9], exec, vcc
	s_mov_b64 exec, s[8:9]
	s_cbranch_execz .LBB0_5
	s_lshl_b32 s8, s95, 8
	s_bcnt1_i32_b64 s6, s[6:7]
	v_mov_b32_e32 v1, s8
	v_mov_b32_e32 v2, s6
	global_atomic_add v1, v2, s[96:97] offset:1024

.LBB0_944:
	s_cmp_lt_u32 s35, 0x40001
	s_mov_b64 s[64:65], 0
	s_cselect_b64 s[66:67], -1, 0
	s_mov_b64 s[74:75], -1
	s_and_b64 vcc, exec, s[66:67]
	s_cbranch_vccz .LBB0_938
	s_branch .LBB0_943
	s_nop 0
.LBB0_945:
	s_or_b64 exec, exec, s[70:71]
	s_and_b64 s[64:65], s[72:73], exec
